# v24 + single taken branch per K-iteration (rare next-tile prefetch block moved out of line, inverted test)
# speedup vs baseline: 1.0030x; 1.0030x over previous
.LBB0_262:
	s_cmp_eq_u32 s65, 28
	s_cselect_b64 s[84:85], -1, 0
	s_and_b64 vcc, s[84:85], s[36:37]
	s_andn2_b64 vcc, exec, vcc
	s_cbranch_vccz .Lrare_ine

.LBB0_286:
	s_cmp_eq_u32 s43, 28
	s_cselect_b64 s[70:71], -1, 0
	s_and_b64 vcc, s[70:71], s[10:11]
	s_andn2_b64 vcc, exec, vcc
	s_cbranch_vccz .Lrare_ino

.LBB0_510:
	s_cmp_eq_u32 s57, 28
	s_cselect_b64 s[70:71], -1, 0
	s_and_b64 s[0:1], s[70:71], s[46:47]
	s_andn2_b64 vcc, exec, s[0:1]
	s_cbranch_vccz .Lrare_out

.LBB0_582:
	s_cmp_eq_u32 s76, 28
	s_cselect_b64 s[64:65], -1, 0
	s_and_b64 s[0:1], s[64:65], s[12:13]
	s_andn2_b64 vcc, exec, s[0:1]
	s_cbranch_vccz .Lrare_gu

.LBB0_646:
	s_cmpk_eq_i32 s41, 0x54
	s_cselect_b64 s[70:71], -1, 0
	s_and_b64 s[0:1], s[70:71], s[50:51]
	s_andn2_b64 vcc, exec, s[0:1]
	s_cbranch_vccz .Lrare_down
